# unitM: next unit's query tile lines touched at the tail of the current unit
# baseline (speedup 1.0000x reference)
; __device__ __forceinline__ unsigned cvtpk(float lo, float hi) { f32x2_t v = {lo, hi}; bf16x2_t b = __builtin_convertvector(v, bf16x2_t); return __builtin_bit_cast(unsigned, b); }
; __device__ __forceinline__ float swap32_add(float v) { auto rr = __builtin_amdgcn_permlane32_swap(__float_as_uint(v), __float_as_uint(v), false, false); return __uint_as_float(rr[0]) + __uint_as_float(rr[1]); }
; __device__ __forceinline__ int crowc(int r) { return (r & 3) + 8 * (r >> 2); }
; template <int D, int DV, bool TAB, bool BITS, int KT> ...
;     ...
;     const float lt = swap32_add(l_run);
;     if (hi == 0) wsf[r32] = 1.0f / fmaxf(lt, 1e-30f);
;     __builtin_amdgcn_fence(__ATOMIC_RELEASE, "wavefront"); __builtin_amdgcn_wave_barrier();
; #pragma unroll
;     for (int j = 0; j < 4; ++j) { const f32x4 a4 = *(const f32x4*)(wsf + 8 * j + 4 * hi);
; #pragma unroll
;         for (int dt = 0; dt < DV / 32; ++dt) { o[dt][4 * j + 0] *= a4[0]; o[dt][4 * j + 1] *= a4[1]; o[dt][4 * j + 2] *= a4[2]; o[dt][4 * j + 3] *= a4[3]; } }
;     __builtin_amdgcn_fence(__ATOMIC_RELEASE, "wavefront"); __builtin_amdgcn_wave_barrier();
; }
; template <int DV>
; __device__ __forceinline__ void attn_store(const f32x16 (&o)[DV / 32], bf16_t* Op, int ldo) {
;     int tid_o = threadIdx.x; asm volatile("" : "+v"(tid_o));
;     const int lane = tid_o & 63, wid = tid_o >> 6, r32 = lane & 31, hi = lane >> 5;
; #pragma unroll
;     for (int dt = 0; dt < DV / 32; ++dt)
; #pragma unroll
;         for (int r = 0; r < 16; ++r) { const int row = 32 * wid + crowc(r) + 4 * hi; Op[(size_t)row * ldo + dt * 32 + r32] = (bf16_t)(cvtpk(o[dt][r], 0.f) & 0xffffu); }
; __global__ void __launch_bounds__(512, 2) fwd_kernel(Args a) {
;     ...
;         for (int it = cb_; it < 2048; it += G) { const int xcd_ = it & 7, jj_ = ((it >> 3) & 31) * 8 + (it >> 8); const int qb = jj_ & 15, rest = xcd_ * 16 + (jj_ >> 4);     unitM(lds, QM, MEMK, MEMVT, MIX, l, rest >> 3, (rest >> 1) & 3, rest & 1, qb); }
.LBB0_1185:
	s_or_b64 exec, exec, s[4:5]
	s_add_i32 s4, s62, s34
	s_cmpk_gt_i32 s4, 0x7ff
	s_cbranch_scc1 .Lpf_m_skip
	v_lshrrev_b32_e32 v106, 1, v228
	v_and_b32_e32 v106, 0xffffffe0, v106
	v_and_or_b32 v106, v228, 31, v106
	v_lshlrev_b32_e32 v106, 11, v106
	v_bfe_u32 v108, v228, 5, 1
	v_lshl_add_u32 v106, v108, 7, v106
	v_add_u32_e32 v106, 0x80000, v106
	v_mov_b32_e32 v107, 0
	v_lshl_add_u64 v[106:107], s[100:101], 0, v[106:107]
	global_load_dword v109, v[106:107], off
	global_load_dword v110, v[106:107], off offset:256
.Lpf_m_skip:
	v_add_u32_e32 v0, s70, v0
	ds_read_b128 v[66:69], v0
	ds_read_b128 v[70:73], v0 offset:32
	s_add_u32 s0, s2, s0
	s_addc_u32 s1, s3, s1
	s_lshl_b32 s4, s63, 1
	s_waitcnt lgkmcnt(1)
	v_mul_f32_e32 v50, v50, v66
	v_mul_f32_e32 v51, v51, v67
	v_mul_f32_e32 v52, v52, v68
	v_mul_f32_e32 v53, v53, v69
	v_mul_f32_e32 v74, v34, v66
	v_mul_f32_e32 v75, v35, v67
	v_mul_f32_e32 v36, v36, v68
	v_mul_f32_e32 v37, v37, v69
	v_mul_f32_e32 v76, v18, v66
	v_mul_f32_e32 v77, v19, v67
	v_mul_f32_e32 v78, v20, v68
	v_mul_f32_e32 v79, v21, v69
	v_mul_f32_e32 v66, v2, v66
	v_mul_f32_e32 v67, v3, v67
	v_mul_f32_e32 v68, v4, v68
	v_mul_f32_e32 v69, v5, v69
	ds_read_b128 v[2:5], v0 offset:64
	s_waitcnt lgkmcnt(1)
	v_mul_f32_e32 v18, v54, v70
	v_mul_f32_e32 v19, v55, v71
	v_mul_f32_e32 v20, v56, v72
	v_mul_f32_e32 v21, v57, v73
	v_mul_f32_e32 v38, v38, v70
	v_mul_f32_e32 v39, v39, v71
	v_mul_f32_e32 v40, v40, v72
	v_mul_f32_e32 v41, v41, v73
	v_mul_f32_e32 v54, v22, v70
	v_mul_f32_e32 v55, v23, v71
	v_mul_f32_e32 v56, v24, v72
	v_mul_f32_e32 v57, v25, v73
	v_mul_f32_e32 v70, v6, v70
	v_mul_f32_e32 v71, v7, v71
	v_mul_f32_e32 v72, v8, v72
	v_mul_f32_e32 v73, v9, v73
	ds_read_b128 v[6:9], v0 offset:96
	v_mov_b32_e32 v0, v228
	s_waitcnt lgkmcnt(1)
	v_mul_f32_e32 v23, v58, v2
	v_mul_f32_e32 v42, v42, v2
	v_mul_f32_e32 v58, v26, v2
	v_mul_f32_e32 v80, v10, v2
	s_add_u32 s0, s0, s4
	v_mul_f32_e32 v25, v59, v3
	v_ashrrev_i32_e32 v2, 1, v0
	v_mul_f32_e32 v43, v43, v3
	v_mul_f32_e32 v59, v27, v3
	v_mul_f32_e32 v81, v11, v3
	s_addc_u32 s1, s1, 0
	s_lshl_b32 s4, s72, 1
	v_and_b32_e32 v3, 31, v0
	v_and_b32_e32 v2, 0xffffffe0, v2
	v_lshrrev_b32_e32 v0, 3, v0
	s_add_u32 s0, s0, s4
	v_and_or_b32 v2, v0, 4, v2
	s_waitcnt lgkmcnt(0)
	v_mul_f32_e32 v64, v64, v8
	v_mul_f32_e32 v48, v48, v8
	v_mul_f32_e32 v86, v32, v8
	v_mul_f32_e32 v90, v16, v8
	s_addc_u32 s1, s1, 0
	v_lshlrev_b32_e32 v0, 1, v3
	v_ashrrev_i32_e32 v3, 31, v2
	v_or_b32_e32 v8, 1, v2
	v_mul_f32_e32 v34, v60, v4
	v_mul_f32_e32 v35, v61, v5
	v_mul_f32_e32 v44, v44, v4
	v_mul_f32_e32 v45, v45, v5
	v_mul_f32_e32 v60, v28, v4
	v_mul_f32_e32 v61, v29, v5
	v_mul_f32_e32 v82, v12, v4
	v_mul_f32_e32 v83, v13, v5
	v_mul_f32_e32 v62, v62, v6
	v_mul_f32_e32 v63, v63, v7
	v_mul_f32_e32 v65, v65, v9
	v_mul_f32_e32 v46, v46, v6
	v_mul_f32_e32 v47, v47, v7
	v_mul_f32_e32 v49, v49, v9
	v_mul_f32_e32 v84, v30, v6
	v_mul_f32_e32 v85, v31, v7
	v_mul_f32_e32 v87, v33, v9
	v_mul_f32_e32 v88, v14, v6
	v_mul_f32_e32 v89, v15, v7
	v_mul_f32_e32 v91, v17, v9
	v_lshl_add_u64 v[4:5], s[0:1], 0, v[0:1]
	v_lshlrev_b64 v[6:7], 11, v[2:3]
	v_ashrrev_i32_e32 v9, 31, v8
	v_or_b32_e32 v10, 2, v2
	v_cvt_pk_bf16_f32 v0, v50, s0
	v_lshl_add_u64 v[6:7], v[4:5], 0, v[6:7]
	v_lshlrev_b64 v[8:9], 11, v[8:9]
	v_ashrrev_i32_e32 v11, 31, v10
	v_or_b32_e32 v12, 3, v2
	global_store_short v[6:7], v0, off
	v_cvt_pk_bf16_f32 v0, v51, s0
	v_lshl_add_u64 v[8:9], v[4:5], 0, v[8:9]
	v_lshlrev_b64 v[10:11], 11, v[10:11]
	v_ashrrev_i32_e32 v13, 31, v12
	v_or_b32_e32 v14, 8, v2
	global_store_short v[8:9], v0, off
	v_cvt_pk_bf16_f32 v0, v52, s0
	v_lshl_add_u64 v[10:11], v[4:5], 0, v[10:11]
	v_lshlrev_b64 v[12:13], 11, v[12:13]
	v_ashrrev_i32_e32 v15, 31, v14
	global_store_short v[10:11], v0, off
	v_cvt_pk_bf16_f32 v0, v53, s0
	v_lshl_add_u64 v[12:13], v[4:5], 0, v[12:13]
	v_lshlrev_b64 v[14:15], 11, v[14:15]
	v_or_b32_e32 v16, 9, v2
	global_store_short v[12:13], v0, off
	v_cvt_pk_bf16_f32 v0, v18, s0
	v_lshl_add_u64 v[14:15], v[4:5], 0, v[14:15]
	v_ashrrev_i32_e32 v17, 31, v16
	v_or_b32_e32 v18, 10, v2
	global_store_short v[14:15], v0, off
	v_cvt_pk_bf16_f32 v0, v19, s0
	v_lshlrev_b64 v[16:17], 11, v[16:17]
	v_ashrrev_i32_e32 v19, 31, v18
	v_lshl_add_u64 v[16:17], v[4:5], 0, v[16:17]
	v_lshlrev_b64 v[18:19], 11, v[18:19]
	global_store_short v[16:17], v0, off
	v_cvt_pk_bf16_f32 v0, v20, s0
	v_lshl_add_u64 v[18:19], v[4:5], 0, v[18:19]
	v_or_b32_e32 v20, 11, v2
	global_store_short v[18:19], v0, off
	v_cvt_pk_bf16_f32 v0, v21, s0
	v_ashrrev_i32_e32 v21, 31, v20
	v_lshlrev_b64 v[20:21], 11, v[20:21]
	v_lshl_add_u64 v[20:21], v[4:5], 0, v[20:21]
	v_or_b32_e32 v22, 16, v2
	global_store_short v[20:21], v0, off
	v_cvt_pk_bf16_f32 v0, v23, s0
	v_ashrrev_i32_e32 v23, 31, v22
	v_lshlrev_b64 v[22:23], 11, v[22:23]
	v_lshl_add_u64 v[22:23], v[4:5], 0, v[22:23]
	v_or_b32_e32 v24, 17, v2
	global_store_short v[22:23], v0, off
	v_cvt_pk_bf16_f32 v0, v25, s0
	v_ashrrev_i32_e32 v25, 31, v24
	v_or_b32_e32 v26, 18, v2
	v_lshlrev_b64 v[24:25], 11, v[24:25]
	v_ashrrev_i32_e32 v27, 31, v26
	v_or_b32_e32 v28, 19, v2
	v_lshl_add_u64 v[24:25], v[4:5], 0, v[24:25]
	v_lshlrev_b64 v[26:27], 11, v[26:27]
	v_ashrrev_i32_e32 v29, 31, v28
	v_or_b32_e32 v30, 24, v2
	global_store_short v[24:25], v0, off
	v_cvt_pk_bf16_f32 v0, v34, s0
	v_lshl_add_u64 v[26:27], v[4:5], 0, v[26:27]
	v_lshlrev_b64 v[28:29], 11, v[28:29]
	v_ashrrev_i32_e32 v31, 31, v30
	v_or_b32_e32 v32, 25, v2
	global_store_short v[26:27], v0, off
	v_cvt_pk_bf16_f32 v0, v35, s0
	v_lshl_add_u64 v[28:29], v[4:5], 0, v[28:29]
	v_lshlrev_b64 v[30:31], 11, v[30:31]
	v_ashrrev_i32_e32 v33, 31, v32
	v_or_b32_e32 v34, 26, v2
; __device__ __forceinline__ unsigned cvtpk(float lo, float hi) { f32x2_t v = {lo, hi}; bf16x2_t b = __builtin_convertvector(v, bf16x2_t); return __builtin_bit_cast(unsigned, b); }
; __device__ __forceinline__ int crowc(int r) { return (r & 3) + 8 * (r >> 2); }
; template <int DV>
; __device__ __forceinline__ void attn_store(const f32x16 (&o)[DV / 32], bf16_t* Op, int ldo) {
;     ...
; #pragma unroll
;     for (int dt = 0; dt < DV / 32; ++dt)
; #pragma unroll
;         for (int r = 0; r < 16; ++r) { const int row = 32 * wid + crowc(r) + 4 * hi; Op[(size_t)row * ldo + dt * 32 + r32] = (bf16_t)(cvtpk(o[dt][r], 0.f) & 0xffffu); }
; __global__ void __launch_bounds__(512, 2) fwd_kernel(Args a) {
;     ...
;         for (int it = cb_; it < 2048; it += G) { const int xcd_ = it & 7, jj_ = ((it >> 3) & 31) * 8 + (it >> 8); const int qb = jj_ & 15, rest = xcd_ * 16 + (jj_ >> 4);     unitM(lds, QM, MEMK, MEMVT, MIX, l, rest >> 3, (rest >> 1) & 3, rest & 1, qb); }
	global_store_short v[28:29], v0, off
	v_cvt_pk_bf16_f32 v0, v62, s0
	v_lshl_add_u64 v[30:31], v[4:5], 0, v[30:31]
	v_lshlrev_b64 v[32:33], 11, v[32:33]
	v_ashrrev_i32_e32 v35, 31, v34
	v_or_b32_e32 v2, 27, v2
	global_store_short v[30:31], v0, off
	v_cvt_pk_bf16_f32 v0, v63, s0
	v_lshl_add_u64 v[32:33], v[4:5], 0, v[32:33]
	v_lshlrev_b64 v[34:35], 11, v[34:35]
	v_ashrrev_i32_e32 v3, 31, v2
	global_store_short v[32:33], v0, off
	v_cvt_pk_bf16_f32 v0, v64, s0
	v_lshl_add_u64 v[34:35], v[4:5], 0, v[34:35]
	v_lshlrev_b64 v[2:3], 11, v[2:3]
	global_store_short v[34:35], v0, off
	v_cvt_pk_bf16_f32 v0, v65, s0
	v_lshl_add_u64 v[2:3], v[4:5], 0, v[2:3]
	global_store_short v[2:3], v0, off
	v_cvt_pk_bf16_f32 v0, v74, s0
	global_store_short v[6:7], v0, off offset:64
	v_cvt_pk_bf16_f32 v0, v75, s0
	global_store_short v[8:9], v0, off offset:64
	v_cvt_pk_bf16_f32 v0, v36, s0
	global_store_short v[10:11], v0, off offset:64
	v_cvt_pk_bf16_f32 v0, v37, s0
	global_store_short v[12:13], v0, off offset:64
	v_cvt_pk_bf16_f32 v0, v38, s0
	global_store_short v[14:15], v0, off offset:64
	v_cvt_pk_bf16_f32 v0, v39, s0
	global_store_short v[16:17], v0, off offset:64
	v_cvt_pk_bf16_f32 v0, v40, s0
	global_store_short v[18:19], v0, off offset:64
	v_cvt_pk_bf16_f32 v0, v41, s0
	global_store_short v[20:21], v0, off offset:64
	v_cvt_pk_bf16_f32 v0, v42, s0
	global_store_short v[22:23], v0, off offset:64
	v_cvt_pk_bf16_f32 v0, v43, s0
	global_store_short v[24:25], v0, off offset:64
	v_cvt_pk_bf16_f32 v0, v44, s0
	global_store_short v[26:27], v0, off offset:64
	v_cvt_pk_bf16_f32 v0, v45, s0
	global_store_short v[28:29], v0, off offset:64
	v_cvt_pk_bf16_f32 v0, v46, s0
	global_store_short v[30:31], v0, off offset:64
	v_cvt_pk_bf16_f32 v0, v47, s0
	global_store_short v[32:33], v0, off offset:64
	v_cvt_pk_bf16_f32 v0, v48, s0
	global_store_short v[34:35], v0, off offset:64
	v_cvt_pk_bf16_f32 v0, v49, s0
	global_store_short v[2:3], v0, off offset:64
	v_cvt_pk_bf16_f32 v0, v76, s0
	global_store_short v[6:7], v0, off offset:128
	v_cvt_pk_bf16_f32 v0, v77, s0
	global_store_short v[8:9], v0, off offset:128
	v_cvt_pk_bf16_f32 v0, v78, s0
	global_store_short v[10:11], v0, off offset:128
	v_cvt_pk_bf16_f32 v0, v79, s0
	global_store_short v[12:13], v0, off offset:128
	v_cvt_pk_bf16_f32 v0, v54, s0
	global_store_short v[14:15], v0, off offset:128
	v_cvt_pk_bf16_f32 v0, v55, s0
	global_store_short v[16:17], v0, off offset:128
	v_cvt_pk_bf16_f32 v0, v56, s0
	global_store_short v[18:19], v0, off offset:128
	v_cvt_pk_bf16_f32 v0, v57, s0
	global_store_short v[20:21], v0, off offset:128
	v_cvt_pk_bf16_f32 v0, v58, s0
	global_store_short v[22:23], v0, off offset:128
	v_cvt_pk_bf16_f32 v0, v59, s0
	global_store_short v[24:25], v0, off offset:128
	v_cvt_pk_bf16_f32 v0, v60, s0
	global_store_short v[26:27], v0, off offset:128
	v_cvt_pk_bf16_f32 v0, v61, s0
	global_store_short v[28:29], v0, off offset:128
	v_cvt_pk_bf16_f32 v0, v84, s0
	global_store_short v[30:31], v0, off offset:128
	v_cvt_pk_bf16_f32 v0, v85, s0
	global_store_short v[32:33], v0, off offset:128
	v_cvt_pk_bf16_f32 v0, v86, s0
	global_store_short v[34:35], v0, off offset:128
	v_cvt_pk_bf16_f32 v0, v87, s0
	global_store_short v[2:3], v0, off offset:128
	v_cvt_pk_bf16_f32 v0, v66, s0
	global_store_short v[6:7], v0, off offset:192
	v_cvt_pk_bf16_f32 v0, v67, s0
	global_store_short v[8:9], v0, off offset:192
	v_cvt_pk_bf16_f32 v0, v68, s0
	global_store_short v[10:11], v0, off offset:192
	v_cvt_pk_bf16_f32 v0, v69, s0
	global_store_short v[12:13], v0, off offset:192
	v_cvt_pk_bf16_f32 v0, v70, s0
	global_store_short v[14:15], v0, off offset:192
	v_cvt_pk_bf16_f32 v0, v71, s0
	global_store_short v[16:17], v0, off offset:192
	v_cvt_pk_bf16_f32 v0, v72, s0
	global_store_short v[18:19], v0, off offset:192
	v_cvt_pk_bf16_f32 v0, v73, s0
	global_store_short v[20:21], v0, off offset:192
	v_cvt_pk_bf16_f32 v0, v80, s0
	global_store_short v[22:23], v0, off offset:192
	v_cvt_pk_bf16_f32 v0, v81, s0
	global_store_short v[24:25], v0, off offset:192
	v_cvt_pk_bf16_f32 v0, v82, s0
	global_store_short v[26:27], v0, off offset:192
	v_cvt_pk_bf16_f32 v0, v83, s0
	global_store_short v[28:29], v0, off offset:192
	v_cvt_pk_bf16_f32 v0, v88, s0
	global_store_short v[30:31], v0, off offset:192
	v_cvt_pk_bf16_f32 v0, v89, s0
	global_store_short v[32:33], v0, off offset:192
	v_cvt_pk_bf16_f32 v0, v90, s0
	s_add_i32 s62, s62, s34
	global_store_short v[34:35], v0, off offset:192
	v_cvt_pk_bf16_f32 v0, v91, s0
	s_cmpk_gt_i32 s62, 0x7ff
	global_store_short v[2:3], v0, off offset:192
	s_cbranch_scc1 .LBB0_1198
; __device__ __forceinline__ unsigned cvtpk(float lo, float hi) { f32x2_t v = {lo, hi}; bf16x2_t b = __builtin_convertvector(v, bf16x2_t); return __builtin_bit_cast(unsigned, b); }
; template <int D, int DV, bool TAB, bool BITS, int KT> ...
;     ...
;     { const bf16_t* qrow = Qp + (size_t)(32 * wid + r32) * ldq + 8 * hi;
; #pragma unroll
;       for (int kk = 0; kk < D / 16; ++kk) { const u32x4v raw = *(const u32x4v*)(qrow + kk * 16); u32x4v sc4;
; #pragma unroll
;           for (int e = 0; e < 4; ++e) { const float lo = __builtin_bit_cast(float, raw[e] << 16) * c2, hh = __builtin_bit_cast(float, raw[e] & 0xffff0000u) * c2; sc4[e] = cvtpk(lo, hh); }
;           qf[kk] = __builtin_bit_cast(bf16x8, sc4); } }
; __device__ __forceinline__ void unitM(unsigned char* lds, const bf16_t* QM, const bf16_t* MK, const bf16_t* MVT, bf16_t* MIX, int l, int b, int h, int half, int qb) {
;     const int q0 = qb * 256; const size_t tokb = (size_t)b * SEQ;
;     f32x16 o[4];
;     attn_pass<256, 128, false, false, 64>(lds, QM + (tokb + q0) * DM + h * 256, DM, MK + (size_t)(b * MEMLEN) * 4096 + l * 1024 + h * 256, 4096,
;                                       MVT + (size_t)(l * 1024 + h * 256 + half * 128) * MMEM + b * MEMLEN, MMEM, nullptr, nullptr, q0, 0, MEMLEN / 64, 1 << 24, 0.0625f * LOG2E, o, false);
;     attn_store<128>(o, MIX + (tokb + q0) * DM + h * 256 + half * 128, DM);
.LBB0_1186:
	s_lshl_b32 s0, s62, 3
	s_and_b32 s13, s0, 0x3c0
	s_and_b32 s0, s62, 0xf8
	s_ashr_i32 s52, s62, 8
	s_add_i32 s6, s0, s52
	s_lshl_b32 s0, s62, 4
	s_and_b32 s0, s0, 0x70
	s_ashr_i32 s8, s6, 4
	s_add_i32 s0, s8, s0
	s_ashr_i32 s4, s0, 3
	s_ashr_i32 s5, s4, 31
	s_lshl_b64 s[0:1], s[4:5], 22
	s_lshl_b32 s5, s6, 18
	s_and_b32 s5, s5, 0x3c0000
	s_or_b32 s0, s0, s5
	s_lshl_b64 s[0:1], s[0:1], 1
	s_add_u32 s5, s46, s0
	s_addc_u32 s7, s47, s1
	s_lshl_b32 s6, s6, 3
	s_and_b32 s63, s6, 0x300
	s_lshl_b32 s9, s63, 1
	s_add_u32 s50, s5, s9
	s_addc_u32 s51, s7, 0
	s_lshl_b32 s6, s4, 8
	s_ashr_i32 s7, s6, 31
	s_lshl_b64 s[4:5], s[6:7], 13
	s_add_u32 s12, s25, s4
	s_addc_u32 s53, s35, s5
	s_add_u32 s70, s12, s9
	s_addc_u32 s71, s53, 0
	s_lshl_b32 s8, s8, 7
	s_or_b32 s9, s24, s63
	s_and_b32 s72, s8, 0x80
	s_or_b32 s8, s9, s72
	s_lshl_b32 s8, s8, 13
	v_readlane_b32 s14, v253, 34
	v_readlane_b32 s15, v253, 35
	s_add_u32 s12, s14, s8
	s_addc_u32 s53, s15, 0
	s_lshl_b64 s[8:9], s[6:7], 1
	v_mov_b32_e32 v13, v228
	s_add_u32 s6, s12, s8
	s_addc_u32 s7, s53, s9
	v_readfirstlane_b32 s12, v13
	s_ashr_i32 s53, s12, 1
	v_mov_b32_e32 v0, s53
	s_movk_i32 s14, 0xffe0
	v_bfi_b32 v2, s14, v0, v13
	v_ashrrev_i32_e32 v3, 31, v2
	v_bfe_u32 v12, v13, 5, 1
	v_lshlrev_b64 v[2:3], 11, v[2:3]
	v_lshl_add_u64 v[2:3], s[50:51], 0, v[2:3]
	s_mov_b64 s[100:101], s[50:51]
	v_lshlrev_b32_e32 v0, 4, v12
	v_lshl_add_u64 v[10:11], v[2:3], 0, v[0:1]
	global_load_dwordx4 v[16:19], v[10:11], off
	global_load_dwordx4 v[20:23], v[10:11], off offset:32
	global_load_dwordx4 v[24:27], v[10:11], off offset:64
	global_load_dwordx4 v[28:31], v[10:11], off offset:96
	global_load_dwordx4 v[32:35], v[10:11], off offset:128
	global_load_dwordx4 v[36:39], v[10:11], off offset:160
	global_load_dwordx4 v[2:5], v[10:11], off offset:192
	global_load_dwordx4 v[6:9], v[10:11], off offset:224
	v_and_b32_e32 v15, 31, v13
	s_lshl_b32 s50, s52, 3
	v_readlane_b32 s14, v255, 17
	s_add_i32 s13, s13, s50
	v_lshlrev_b32_e32 v14, 3, v12
	s_bfe_u32 s13, s13, 0x20008
	s_and_b32 s12, s12, 0x3fffffc0
	s_lshl_b32 s50, s13, 8
	s_mov_b32 s73, 3
	v_mov_b32_e32 v220, 0
	v_mov_b32_e32 v205, 0
	s_waitcnt vmcnt(0)
	v_lshlrev_b32_e32 v40, 16, v16
	v_and_b32_e32 v41, 0xffff0000, v16
	v_lshlrev_b32_e32 v16, 16, v17
	v_and_b32_e32 v17, 0xffff0000, v17
	v_lshlrev_b32_e32 v42, 16, v18
	v_and_b32_e32 v43, 0xffff0000, v18
	v_lshlrev_b32_e32 v18, 16, v19
	v_and_b32_e32 v19, 0xffff0000, v19
	v_lshlrev_b32_e32 v44, 16, v20
	v_and_b32_e32 v45, 0xffff0000, v20
	v_lshlrev_b32_e32 v20, 16, v21
	v_and_b32_e32 v21, 0xffff0000, v21
	v_pk_mul_f32 v[16:17], v[16:17], s[36:37] op_sel_hi:[1,0]
	v_pk_mul_f32 v[18:19], v[18:19], s[36:37] op_sel_hi:[1,0]
	v_lshlrev_b32_e32 v52, 16, v28
	v_and_b32_e32 v53, 0xffff0000, v28
	v_lshlrev_b32_e32 v28, 16, v29
	v_pk_mul_f32 v[20:21], v[20:21], s[36:37] op_sel_hi:[1,0]
	v_cvt_pk_bf16_f32 v111, v16, v17
	v_cvt_pk_bf16_f32 v113, v18, v19
	global_load_dwordx4 v[16:19], v[10:11], off offset:256
	v_and_b32_e32 v29, 0xffff0000, v29
	v_cvt_pk_bf16_f32 v107, v20, v21
	v_pk_mul_f32 v[20:21], v[28:29], s[36:37] op_sel_hi:[1,0]
	v_lshlrev_b32_e32 v46, 16, v22
	v_cvt_pk_bf16_f32 v99, v20, v21
	v_lshlrev_b32_e32 v20, 16, v30
	v_and_b32_e32 v21, 0xffff0000, v30
	v_pk_mul_f32 v[20:21], v[20:21], s[36:37] op_sel_hi:[1,0]
	v_and_b32_e32 v47, 0xffff0000, v22
	v_cvt_pk_bf16_f32 v100, v20, v21
	v_lshlrev_b32_e32 v20, 16, v31
	v_and_b32_e32 v21, 0xffff0000, v31
	v_pk_mul_f32 v[20:21], v[20:21], s[36:37] op_sel_hi:[1,0]
	v_lshlrev_b32_e32 v22, 16, v23
	v_and_b32_e32 v23, 0xffff0000, v23
	v_cvt_pk_bf16_f32 v101, v20, v21
	v_lshlrev_b32_e32 v20, 16, v32
	v_and_b32_e32 v21, 0xffff0000, v32
	v_lshlrev_b32_e32 v48, 16, v24
	v_and_b32_e32 v49, 0xffff0000, v24
	v_lshlrev_b32_e32 v24, 16, v25
	v_and_b32_e32 v25, 0xffff0000, v25
	v_pk_mul_f32 v[22:23], v[22:23], s[36:37] op_sel_hi:[1,0]
	v_pk_mul_f32 v[20:21], v[20:21], s[36:37] op_sel_hi:[1,0]
	v_pk_mul_f32 v[24:25], v[24:25], s[36:37] op_sel_hi:[1,0]
	v_cvt_pk_bf16_f32 v109, v22, v23
	v_cvt_pk_bf16_f32 v114, v20, v21
	global_load_dwordx4 v[20:23], v[10:11], off offset:288
	v_cvt_pk_bf16_f32 v103, v24, v25
	v_lshlrev_b32_e32 v24, 16, v33
	v_and_b32_e32 v25, 0xffff0000, v33
	v_pk_mul_f32 v[24:25], v[24:25], s[36:37] op_sel_hi:[1,0]
	v_lshlrev_b32_e32 v50, 16, v26
	v_cvt_pk_bf16_f32 v115, v24, v25
	v_lshlrev_b32_e32 v24, 16, v34
	v_and_b32_e32 v25, 0xffff0000, v34
	v_pk_mul_f32 v[24:25], v[24:25], s[36:37] op_sel_hi:[1,0]
	v_and_b32_e32 v51, 0xffff0000, v26
	v_cvt_pk_bf16_f32 v116, v24, v25
	v_lshlrev_b32_e32 v24, 16, v35
	v_and_b32_e32 v25, 0xffff0000, v35
	v_lshlrev_b32_e32 v26, 16, v27
	v_and_b32_e32 v27, 0xffff0000, v27
	v_pk_mul_f32 v[24:25], v[24:25], s[36:37] op_sel_hi:[1,0]
	v_pk_mul_f32 v[26:27], v[26:27], s[36:37] op_sel_hi:[1,0]
	v_cvt_pk_bf16_f32 v117, v24, v25
	v_lshlrev_b32_e32 v24, 16, v36
	v_and_b32_e32 v25, 0xffff0000, v36
	v_cvt_pk_bf16_f32 v105, v26, v27
	v_pk_mul_f32 v[28:29], v[24:25], s[36:37] op_sel_hi:[1,0]
	global_load_dwordx4 v[24:27], v[10:11], off offset:320
	v_cvt_pk_bf16_f32 v118, v28, v29
	v_lshlrev_b32_e32 v28, 16, v37
	v_and_b32_e32 v29, 0xffff0000, v37
	v_pk_mul_f32 v[28:29], v[28:29], s[36:37] op_sel_hi:[1,0]
	v_lshlrev_b32_e32 v32, 16, v2
	v_cvt_pk_bf16_f32 v119, v28, v29
	v_lshlrev_b32_e32 v28, 16, v38
	v_and_b32_e32 v29, 0xffff0000, v38
	v_pk_mul_f32 v[28:29], v[28:29], s[36:37] op_sel_hi:[1,0]
	v_and_b32_e32 v33, 0xffff0000, v2
	v_cvt_pk_bf16_f32 v120, v28, v29
	v_lshlrev_b32_e32 v28, 16, v39
	v_and_b32_e32 v29, 0xffff0000, v39
	v_pk_mul_f32 v[28:29], v[28:29], s[36:37] op_sel_hi:[1,0]
	v_lshlrev_b32_e32 v2, 16, v3
	v_cvt_pk_bf16_f32 v121, v28, v29
	global_load_dwordx4 v[28:31], v[10:11], off offset:352
	v_and_b32_e32 v3, 0xffff0000, v3
	v_pk_mul_f32 v[2:3], v[2:3], s[36:37] op_sel_hi:[1,0]
	v_pk_mul_f32 v[32:33], v[32:33], s[36:37] op_sel_hi:[1,0]
	v_cvt_pk_bf16_f32 v123, v2, v3
	v_lshlrev_b32_e32 v2, 16, v4
	v_and_b32_e32 v3, 0xffff0000, v4
	v_pk_mul_f32 v[2:3], v[2:3], s[36:37] op_sel_hi:[1,0]
	v_cvt_pk_bf16_f32 v122, v32, v33
	v_cvt_pk_bf16_f32 v124, v2, v3
	v_lshlrev_b32_e32 v2, 16, v5
	v_and_b32_e32 v3, 0xffff0000, v5
	v_pk_mul_f32 v[2:3], v[2:3], s[36:37] op_sel_hi:[1,0]
	v_lshlrev_b32_e32 v32, 16, v6
	v_cvt_pk_bf16_f32 v125, v2, v3
	global_load_dwordx4 v[2:5], v[10:11], off offset:384
	v_and_b32_e32 v33, 0xffff0000, v6
	v_lshlrev_b32_e32 v6, 16, v7
	v_and_b32_e32 v7, 0xffff0000, v7
	v_pk_mul_f32 v[6:7], v[6:7], s[36:37] op_sel_hi:[1,0]
	v_pk_mul_f32 v[40:41], v[40:41], s[36:37] op_sel_hi:[1,0]
	v_cvt_pk_bf16_f32 v127, v6, v7
	v_lshlrev_b32_e32 v6, 16, v8
	v_and_b32_e32 v7, 0xffff0000, v8
	v_pk_mul_f32 v[6:7], v[6:7], s[36:37] op_sel_hi:[1,0]
	v_cvt_pk_bf16_f32 v110, v40, v41
	v_cvt_pk_bf16_f32 v128, v6, v7
	v_lshlrev_b32_e32 v6, 16, v9
	v_and_b32_e32 v7, 0xffff0000, v9
	v_pk_mul_f32 v[6:7], v[6:7], s[36:37] op_sel_hi:[1,0]
	v_ashrrev_i32_e32 v40, 31, v13
	v_cvt_pk_bf16_f32 v129, v6, v7
	s_waitcnt vmcnt(4)
; __device__ __forceinline__ unsigned cvtpk(float lo, float hi) { f32x2_t v = {lo, hi}; bf16x2_t b = __builtin_convertvector(v, bf16x2_t); return __builtin_bit_cast(unsigned, b); }
; template <int D, int DV, bool TAB, bool BITS, int KT> ...
;     ...
;     { const bf16_t* qrow = Qp + (size_t)(32 * wid + r32) * ldq + 8 * hi;
; #pragma unroll
;       for (int kk = 0; kk < D / 16; ++kk) { const u32x4v raw = *(const u32x4v*)(qrow + kk * 16); u32x4v sc4;
; #pragma unroll
;           for (int e = 0; e < 4; ++e) { const float lo = __builtin_bit_cast(float, raw[e] << 16) * c2, hh = __builtin_bit_cast(float, raw[e] & 0xffff0000u) * c2; sc4[e] = cvtpk(lo, hh); }
;           qf[kk] = __builtin_bit_cast(bf16x8, sc4); } }
; #pragma unroll
;     for (int dt = 0; dt < DV / 32; ++dt)
; #pragma unroll
;         for (int r = 0; r < 16; ++r) o[dt][r] = 0.f;
;     float mhat = 0.f, l_run = 0.f;
;     const int qpos = q0 + 32 * wid + r32, qw_lo = q0 + 32 * wid, qw_hi = qw_lo + 31;
;     u32x4v kreg[NKC], vreg[NVC];
;     ...
;     AT_LOAD(t_lo); AT_STORE(0);
	v_lshlrev_b32_e32 v6, 16, v16
	v_and_b32_e32 v7, 0xffff0000, v16
	v_pk_mul_f32 v[6:7], v[6:7], s[36:37] op_sel_hi:[1,0]
	v_pk_mul_f32 v[44:45], v[44:45], s[36:37] op_sel_hi:[1,0]
	v_cvt_pk_bf16_f32 v130, v6, v7
	v_lshlrev_b32_e32 v6, 16, v17
	v_and_b32_e32 v7, 0xffff0000, v17
	v_pk_mul_f32 v[6:7], v[6:7], s[36:37] op_sel_hi:[1,0]
	v_pk_mul_f32 v[32:33], v[32:33], s[36:37] op_sel_hi:[1,0]
	v_cvt_pk_bf16_f32 v131, v6, v7
	v_lshlrev_b32_e32 v6, 16, v18
	v_and_b32_e32 v7, 0xffff0000, v18
	v_pk_mul_f32 v[6:7], v[6:7], s[36:37] op_sel_hi:[1,0]
	v_pk_mul_f32 v[48:49], v[48:49], s[36:37] op_sel_hi:[1,0]
	v_cvt_pk_bf16_f32 v132, v6, v7
	v_lshlrev_b32_e32 v6, 16, v19
	v_and_b32_e32 v7, 0xffff0000, v19
	v_pk_mul_f32 v[6:7], v[6:7], s[36:37] op_sel_hi:[1,0]
	v_cvt_pk_bf16_f32 v106, v44, v45
	v_cvt_pk_bf16_f32 v133, v6, v7
	s_waitcnt vmcnt(3)
	v_lshlrev_b32_e32 v6, 16, v20
	v_and_b32_e32 v7, 0xffff0000, v20
	v_pk_mul_f32 v[6:7], v[6:7], s[36:37] op_sel_hi:[1,0]
	v_cvt_pk_bf16_f32 v126, v32, v33
	v_cvt_pk_bf16_f32 v134, v6, v7
	v_lshlrev_b32_e32 v6, 16, v21
	v_and_b32_e32 v7, 0xffff0000, v21
	v_pk_mul_f32 v[6:7], v[6:7], s[36:37] op_sel_hi:[1,0]
	v_add_u32_e32 v32, 0x400, v13
	v_cvt_pk_bf16_f32 v135, v6, v7
	v_lshlrev_b32_e32 v6, 16, v22
	v_and_b32_e32 v7, 0xffff0000, v22
	v_pk_mul_f32 v[6:7], v[6:7], s[36:37] op_sel_hi:[1,0]
	v_cvt_pk_bf16_f32 v102, v48, v49
	v_cvt_pk_bf16_f32 v136, v6, v7
	v_lshlrev_b32_e32 v6, 16, v23
	v_and_b32_e32 v7, 0xffff0000, v23
	v_pk_mul_f32 v[6:7], v[6:7], s[36:37] op_sel_hi:[1,0]
	v_ashrrev_i32_e32 v33, 31, v32
	v_cvt_pk_bf16_f32 v137, v6, v7
	s_waitcnt vmcnt(2)
	v_lshlrev_b32_e32 v6, 16, v24
	v_and_b32_e32 v7, 0xffff0000, v24
	v_pk_mul_f32 v[6:7], v[6:7], s[36:37] op_sel_hi:[1,0]
	v_pk_mul_f32 v[50:51], v[50:51], s[36:37] op_sel_hi:[1,0]
	v_cvt_pk_bf16_f32 v138, v6, v7
	v_lshlrev_b32_e32 v6, 16, v25
	v_and_b32_e32 v7, 0xffff0000, v25
	v_pk_mul_f32 v[6:7], v[6:7], s[36:37] op_sel_hi:[1,0]
	v_lshrrev_b32_e32 v33, 27, v33
	v_cvt_pk_bf16_f32 v139, v6, v7
	v_lshlrev_b32_e32 v6, 16, v26
	v_and_b32_e32 v7, 0xffff0000, v26
	v_pk_mul_f32 v[6:7], v[6:7], s[36:37] op_sel_hi:[1,0]
	v_cvt_pk_bf16_f32 v104, v50, v51
	v_cvt_pk_bf16_f32 v140, v6, v7
	v_lshlrev_b32_e32 v6, 16, v27
	v_and_b32_e32 v7, 0xffff0000, v27
	v_pk_mul_f32 v[6:7], v[6:7], s[36:37] op_sel_hi:[1,0]
	v_add_u32_e32 v33, v32, v33
	v_cvt_pk_bf16_f32 v141, v6, v7
	s_waitcnt vmcnt(1)
	v_lshlrev_b32_e32 v6, 16, v28
	v_and_b32_e32 v7, 0xffff0000, v28
	v_pk_mul_f32 v[6:7], v[6:7], s[36:37] op_sel_hi:[1,0]
	v_pk_mul_f32 v[52:53], v[52:53], s[36:37] op_sel_hi:[1,0]
	v_cvt_pk_bf16_f32 v142, v6, v7
	v_lshlrev_b32_e32 v6, 16, v29
	v_and_b32_e32 v7, 0xffff0000, v29
	v_pk_mul_f32 v[6:7], v[6:7], s[36:37] op_sel_hi:[1,0]
	v_ashrrev_i32_e32 v56, 5, v33
	v_cvt_pk_bf16_f32 v143, v6, v7
	v_lshlrev_b32_e32 v6, 16, v30
	v_and_b32_e32 v7, 0xffff0000, v30
	v_pk_mul_f32 v[6:7], v[6:7], s[36:37] op_sel_hi:[1,0]
	v_and_b32_e32 v33, 0xffffffe0, v33
	v_cvt_pk_bf16_f32 v144, v6, v7
	v_lshlrev_b32_e32 v6, 16, v31
	v_and_b32_e32 v7, 0xffff0000, v31
	v_pk_mul_f32 v[6:7], v[6:7], s[36:37] op_sel_hi:[1,0]
	v_cvt_pk_bf16_f32 v98, v52, v53
	v_cvt_pk_bf16_f32 v145, v6, v7
	global_load_dwordx4 v[6:9], v[10:11], off offset:416
	s_waitcnt vmcnt(1)
	v_lshlrev_b32_e32 v16, 16, v2
	v_and_b32_e32 v17, 0xffff0000, v2
	v_lshlrev_b32_e32 v2, 16, v3
	v_and_b32_e32 v3, 0xffff0000, v3
	v_pk_mul_f32 v[2:3], v[2:3], s[36:37] op_sel_hi:[1,0]
	v_pk_mul_f32 v[16:17], v[16:17], s[36:37] op_sel_hi:[1,0]
	v_cvt_pk_bf16_f32 v147, v2, v3
	v_lshrrev_b32_e32 v2, 27, v40
	v_add_u32_e32 v3, v13, v2
	v_ashrrev_i32_e32 v2, 5, v3
	v_and_b32_e32 v3, 0xffffffe0, v3
	v_sub_u32_e32 v82, v13, v3
	v_ashrrev_i32_e32 v3, 31, v2
	v_cvt_pk_bf16_f32 v146, v16, v17
	global_load_dwordx4 v[16:19], v[10:11], off offset:448
	global_load_dwordx4 v[20:23], v[10:11], off offset:480
	v_lshlrev_b64 v[10:11], 13, v[2:3]
	v_lshlrev_b32_e32 v26, 3, v82
	v_add_u32_e32 v3, 0x200, v13
	v_ashrrev_i32_e32 v27, 31, v26
	v_ashrrev_i32_e32 v44, 31, v3
	v_lshlrev_b64 v[48:49], 1, v[26:27]
	v_lshrrev_b32_e32 v26, 27, v44
	v_add_u32_e32 v26, v3, v26
	v_ashrrev_i32_e32 v50, 5, v26
	v_ashrrev_i32_e32 v51, 31, v50
	v_lshlrev_b64 v[52:53], 13, v[50:51]
	v_sub_u32_e32 v51, v32, v33
	v_lshlrev_b32_e32 v34, 3, v51
	v_ashrrev_i32_e32 v35, 31, v34
	v_lshlrev_b64 v[60:61], 1, v[34:35]
	v_add_u32_e32 v34, 0x600, v13
	v_ashrrev_i32_e32 v35, 31, v34
	v_and_b32_e32 v26, 0xffffffe0, v26
	v_lshrrev_b32_e32 v35, 27, v35
	v_sub_u32_e32 v83, v3, v26
	v_add_u32_e32 v35, v34, v35
	v_lshrrev_b32_e32 v40, 29, v40
	v_lshlrev_b32_e32 v28, 3, v83
	v_ashrrev_i32_e32 v57, 31, v56
	v_ashrrev_i32_e32 v62, 5, v35
	v_and_b32_e32 v35, 0xffffffe0, v35
	v_add_u32_e32 v40, v13, v40
	v_ashrrev_i32_e32 v29, 31, v28
	v_lshlrev_b64 v[58:59], 13, v[56:57]
	v_sub_u32_e32 v57, v34, v35
	v_ashrrev_i32_e32 v68, 3, v40
	v_and_b32_e32 v40, -8, v40
	v_pk_mul_f32 v[42:43], v[42:43], s[36:37] op_sel_hi:[1,0]
	v_lshl_add_u64 v[24:25], s[70:71], 0, v[10:11]
	v_lshl_add_u64 v[26:27], s[70:71], 0, v[52:53]
	v_lshlrev_b64 v[54:55], 1, v[28:29]
	v_ashrrev_i32_e32 v63, 31, v62
	v_lshlrev_b32_e32 v36, 3, v57
	v_sub_u32_e32 v13, v13, v40
	v_cvt_pk_bf16_f32 v112, v42, v43
	v_lshl_add_u64 v[24:25], v[24:25], 0, v[48:49]
	v_lshl_add_u64 v[28:29], v[26:27], 0, v[54:55]
	v_lshlrev_b64 v[64:65], 13, v[62:63]
	v_ashrrev_i32_e32 v37, 31, v36
	v_ashrrev_i32_e32 v69, 31, v68
	v_lshlrev_b32_e32 v42, 3, v13
	global_load_dwordx4 v[24:27], v[24:25], off
	s_nop 0
	global_load_dwordx4 v[28:31], v[28:29], off
	v_lshl_add_u64 v[32:33], s[70:71], 0, v[58:59]
	v_lshl_add_u64 v[34:35], s[70:71], 0, v[64:65]
	v_lshlrev_b64 v[66:67], 1, v[36:37]
	v_lshlrev_b64 v[70:71], 13, v[68:69]
	v_ashrrev_i32_e32 v43, 31, v42
	v_lshrrev_b32_e32 v44, 29, v44
	v_lshl_add_u64 v[32:33], v[32:33], 0, v[60:61]
	v_lshl_add_u64 v[36:37], v[34:35], 0, v[66:67]
	v_lshl_add_u64 v[40:41], s[6:7], 0, v[70:71]
	v_lshlrev_b64 v[72:73], 1, v[42:43]
	v_add_u32_e32 v44, v3, v44
	global_load_dwordx4 v[32:35], v[32:33], off
	s_nop 0
	global_load_dwordx4 v[36:39], v[36:37], off
	v_lshl_add_u64 v[40:41], v[40:41], 0, v[72:73]
	v_ashrrev_i32_e32 v74, 3, v44
	v_and_b32_e32 v44, -8, v44
	v_pk_mul_f32 v[46:47], v[46:47], s[36:37] op_sel_hi:[1,0]
	global_load_dwordx4 v[40:43], v[40:41], off
	v_sub_u32_e32 v3, v3, v44
	v_cvt_pk_bf16_f32 v108, v46, v47
	v_ashrrev_i32_e32 v75, 31, v74
	v_lshlrev_b32_e32 v46, 3, v3
	v_lshlrev_b64 v[76:77], 13, v[74:75]
	v_ashrrev_i32_e32 v47, 31, v46
	v_lshl_add_u64 v[44:45], s[6:7], 0, v[76:77]
	v_lshlrev_b64 v[78:79], 1, v[46:47]
	v_lshl_add_u64 v[44:45], v[44:45], 0, v[78:79]
	global_load_dwordx4 v[44:47], v[44:45], off
	v_lshlrev_b32_e32 v80, 16, v4
	v_and_b32_e32 v81, 0xffff0000, v4
	v_lshlrev_b32_e32 v4, 16, v5
	v_and_b32_e32 v5, 0xffff0000, v5
	v_pk_mul_f32 v[4:5], v[4:5], s[36:37] op_sel_hi:[1,0]
	s_movk_i32 s6, 0x210
	v_cvt_pk_bf16_f32 v149, v4, v5
	s_waitcnt vmcnt(8)
; __device__ __forceinline__ unsigned cvtpk(float lo, float hi) { f32x2_t v = {lo, hi}; bf16x2_t b = __builtin_convertvector(v, bf16x2_t); return __builtin_bit_cast(unsigned, b); }
; template <int D, int DV, bool TAB, bool BITS, int KT> ...
;     ...
;     { const bf16_t* qrow = Qp + (size_t)(32 * wid + r32) * ldq + 8 * hi;
; #pragma unroll
;       for (int kk = 0; kk < D / 16; ++kk) { const u32x4v raw = *(const u32x4v*)(qrow + kk * 16); u32x4v sc4;
; #pragma unroll
;           for (int e = 0; e < 4; ++e) { const float lo = __builtin_bit_cast(float, raw[e] << 16) * c2, hh = __builtin_bit_cast(float, raw[e] & 0xffff0000u) * c2; sc4[e] = cvtpk(lo, hh); }
;           qf[kk] = __builtin_bit_cast(bf16x8, sc4); } }
; #pragma unroll
;     for (int dt = 0; dt < DV / 32; ++dt)
; #pragma unroll
;         for (int r = 0; r < 16; ++r) o[dt][r] = 0.f;
;     float mhat = 0.f, l_run = 0.f;
;     const int qpos = q0 + 32 * wid + r32, qw_lo = q0 + 32 * wid, qw_hi = qw_lo + 31;
;     u32x4v kreg[NKC], vreg[NVC];
;     ...
;     AT_LOAD(t_lo); AT_STORE(0);
;     unsigned wq[NBW], wn[NBW];
;     const unsigned* bprow = BITS ? bitsp + (size_t)(32 * wid + r32) * 128 : nullptr;
; #pragma unroll
;     for (int i = 0; i < NBW; ++i) { wq[i] = 0xffffffffu; wn[i] = 0xffffffffu; if (BITS) wq[i] = bprow[NBW * t_lo + i]; }
;     __syncthreads();
	v_lshlrev_b32_e32 v4, 16, v6
	v_and_b32_e32 v5, 0xffff0000, v6
	v_pk_mul_f32 v[4:5], v[4:5], s[36:37] op_sel_hi:[1,0]
	v_mul_lo_u32 v208, v2, s6
	v_cvt_pk_bf16_f32 v150, v4, v5
	v_lshlrev_b32_e32 v4, 16, v7
	v_and_b32_e32 v5, 0xffff0000, v7
	v_lshlrev_b32_e32 v209, 4, v82
	v_pk_mul_f32 v[4:5], v[4:5], s[36:37] op_sel_hi:[1,0]
	v_add3_u32 v2, 0, v208, v209
	v_mul_lo_u32 v210, v50, s6
	v_lshlrev_b32_e32 v211, 4, v83
	v_cvt_pk_bf16_f32 v151, v4, v5
	v_lshlrev_b32_e32 v4, 16, v8
	v_and_b32_e32 v5, 0xffff0000, v8
	v_mul_lo_u32 v212, v56, s6
	v_lshlrev_b32_e32 v213, 4, v51
	v_pk_mul_f32 v[4:5], v[4:5], s[36:37] op_sel_hi:[1,0]
	v_mul_lo_u32 v214, v62, s6
	v_lshlrev_b32_e32 v215, 4, v57
	s_movk_i32 s6, 0x88
	v_cvt_pk_bf16_f32 v152, v4, v5
	v_lshlrev_b32_e32 v4, 16, v9
	v_and_b32_e32 v5, 0xffff0000, v9
	v_mul_lo_u32 v216, v68, s6
	v_lshlrev_b32_e32 v217, 4, v13
	v_pk_mul_f32 v[4:5], v[4:5], s[36:37] op_sel_hi:[1,0]
	v_mul_lo_u32 v218, v74, s6
	v_lshlrev_b32_e32 v219, 4, v3
	v_mul_u32_u24_e32 v3, 0x88, v15
	v_cvt_pk_bf16_f32 v153, v4, v5
	s_waitcnt vmcnt(7)
	v_lshlrev_b32_e32 v4, 16, v16
	v_and_b32_e32 v5, 0xffff0000, v16
	v_add3_u32 v206, s14, v14, v3
	v_pk_mul_f32 v[4:5], v[4:5], s[36:37] op_sel_hi:[1,0]
	s_lshl_b32 s6, s12, 2
	v_cvt_pk_bf16_f32 v154, v4, v5
	v_lshlrev_b32_e32 v4, 16, v17
	v_and_b32_e32 v5, 0xffff0000, v17
	s_add_i32 s70, s6, 0
	v_pk_mul_f32 v[4:5], v[4:5], s[36:37] op_sel_hi:[1,0]
	s_add_i32 s70, s70, 0x1d400
	v_cvt_pk_bf16_f32 v155, v4, v5
	v_lshlrev_b32_e32 v4, 16, v18
	s_waitcnt vmcnt(5)
	ds_write_b128 v2, v[24:27]
	v_add3_u32 v2, 0, v210, v211
	s_waitcnt vmcnt(4)
	ds_write_b128 v2, v[28:31]
	v_add3_u32 v2, 0, v212, v213
	v_and_b32_e32 v5, 0xffff0000, v18
	v_pk_mul_f32 v[4:5], v[4:5], s[36:37] op_sel_hi:[1,0]
	v_mov_b32_e32 v16, v1
	v_cvt_pk_bf16_f32 v156, v4, v5
	v_lshlrev_b32_e32 v4, 16, v19
	v_and_b32_e32 v5, 0xffff0000, v19
	v_pk_mul_f32 v[4:5], v[4:5], s[36:37] op_sel_hi:[1,0]
	v_mov_b32_e32 v17, v1
	s_waitcnt vmcnt(3)
	ds_write_b128 v2, v[32:35]
	v_add3_u32 v2, 0, v214, v215
	s_waitcnt vmcnt(2)
	ds_write_b128 v2, v[36:39]
	v_add3_u32 v2, s14, v216, v217
	v_cvt_pk_bf16_f32 v157, v4, v5
	v_lshlrev_b32_e32 v4, 16, v20
	s_waitcnt vmcnt(1)
	ds_write2_b64 v2, v[40:41], v[42:43] offset1:1
	v_add3_u32 v2, s14, v218, v219
	v_readlane_b32 s14, v255, 18
	s_add_i32 s50, s14, s50
	s_add_i32 s64, s50, s72
	s_lshl_b64 s[50:51], s[64:65], 13
	s_add_u32 s8, s8, s50
	s_addc_u32 s9, s9, s51
	s_mov_b64 s[14:15], 0x3aa00080
	v_and_b32_e32 v5, 0xffff0000, v20
	s_waitcnt vmcnt(0)
	ds_write2_b64 v2, v[44:45], v[46:47] offset1:1
	v_mul_u32_u24_e32 v2, 0x210, v15
	v_add3_u32 v207, 0, v2, v0
	v_lshl_add_u64 v[2:3], v[70:71], 0, s[8:9]
	v_lshl_add_u64 v[2:3], v[2:3], 0, v[72:73]
	v_lshl_add_u64 v[192:193], v[2:3], 0, s[14:15]
	v_lshl_add_u64 v[2:3], v[76:77], 0, s[8:9]
	s_lshl_b32 s8, s13, 9
	v_pk_mul_f32 v[4:5], v[4:5], s[36:37] op_sel_hi:[1,0]
	s_or_b32 s4, s4, s8
	v_readlane_b32 s8, v255, 19
	v_cvt_pk_bf16_f32 v158, v4, v5
	v_lshlrev_b32_e32 v4, 16, v21
	v_and_b32_e32 v5, 0xffff0000, v21
	v_readlane_b32 s9, v255, 20
	s_add_u32 s4, s4, s8
	v_pk_mul_f32 v[4:5], v[4:5], s[36:37] op_sel_hi:[1,0]
	v_lshl_add_u64 v[2:3], v[2:3], 0, v[78:79]
	s_addc_u32 s5, s5, s9
	v_cvt_pk_bf16_f32 v159, v4, v5
	v_lshlrev_b32_e32 v4, 16, v22
	v_and_b32_e32 v5, 0xffff0000, v22
	v_lshl_add_u64 v[194:195], v[2:3], 0, s[14:15]
	v_lshl_add_u64 v[2:3], s[4:5], 0, v[64:65]
	v_pk_mul_f32 v[4:5], v[4:5], s[36:37] op_sel_hi:[1,0]
	v_lshl_add_u64 v[196:197], v[2:3], 0, v[66:67]
	v_lshl_add_u64 v[2:3], s[4:5], 0, v[58:59]
	v_cvt_pk_bf16_f32 v160, v4, v5
	v_lshlrev_b32_e32 v4, 16, v23
	v_and_b32_e32 v5, 0xffff0000, v23
	v_lshl_add_u64 v[198:199], v[2:3], 0, v[60:61]
	v_lshl_add_u64 v[2:3], s[4:5], 0, v[52:53]
	v_pk_mul_f32 v[4:5], v[4:5], s[36:37] op_sel_hi:[1,0]
	v_lshl_add_u64 v[200:201], v[2:3], 0, v[54:55]
	v_lshl_add_u64 v[2:3], s[4:5], 0, v[10:11]
	v_pk_mul_f32 v[80:81], v[80:81], s[36:37] op_sel_hi:[1,0]
	v_cvt_pk_bf16_f32 v161, v4, v5
	v_cmp_eq_u32_e64 s[6:7], 0, v12
	v_lshl_add_u32 v187, v15, 2, s70
	v_lshl_add_u64 v[202:203], v[2:3], 0, v[48:49]
	v_mov_b32_e32 v2, v1
	v_mov_b32_e32 v3, v1
	v_mov_b32_e32 v4, v1
	v_mov_b32_e32 v5, v1
	v_mov_b32_e32 v6, v1
	v_mov_b32_e32 v7, v1
	v_mov_b32_e32 v8, v1
	v_mov_b32_e32 v9, v1
	v_mov_b32_e32 v10, v1
	v_mov_b32_e32 v11, v1
	v_mov_b32_e32 v12, v1
	v_mov_b32_e32 v13, v1
	v_mov_b32_e32 v14, v1
	v_mov_b32_e32 v15, v1
	v_mov_b64_e32 v[32:33], v[16:17]
	v_mov_b64_e32 v[48:49], v[16:17]
	v_mov_b64_e32 v[64:65], v[16:17]
	v_cvt_pk_bf16_f32 v148, v80, v81
	s_mov_b32 s12, 0
	v_mov_b64_e32 v[30:31], v[14:15]
	v_mov_b64_e32 v[28:29], v[12:13]
	v_mov_b64_e32 v[26:27], v[10:11]
	v_mov_b64_e32 v[24:25], v[8:9]
	v_mov_b64_e32 v[22:23], v[6:7]
	v_mov_b64_e32 v[20:21], v[4:5]
	v_mov_b64_e32 v[18:19], v[2:3]
	v_mov_b64_e32 v[46:47], v[14:15]
	v_mov_b64_e32 v[44:45], v[12:13]
	v_mov_b64_e32 v[42:43], v[10:11]
	v_mov_b64_e32 v[40:41], v[8:9]
	v_mov_b64_e32 v[38:39], v[6:7]
	v_mov_b64_e32 v[36:37], v[4:5]
	v_mov_b64_e32 v[34:35], v[2:3]
	v_mov_b64_e32 v[62:63], v[14:15]
	v_mov_b64_e32 v[60:61], v[12:13]
	v_mov_b64_e32 v[58:59], v[10:11]
	v_mov_b64_e32 v[56:57], v[8:9]
	v_mov_b64_e32 v[54:55], v[6:7]
	v_mov_b64_e32 v[52:53], v[4:5]
	v_mov_b64_e32 v[50:51], v[2:3]
	s_waitcnt lgkmcnt(0)
	s_barrier
	s_branch .LBB0_1189
